# refined nt loads + gates2 MFMA loop: 16 loads of each 8-kstep group issued together with counted vmcnt instead of 32 serialized round trips
# baseline (speedup 1.0000x reference)
; DI void phase_gates2(const Params& p, unsigned char* smem, int layer, const bf16_t* xin, int nchunks, int tid) {
;     ...
;             for (int ks = 0; ks < 32; ++ks) {
;                 const bf16x8 av = *(const bf16x8*)(ap + ks * 32), bv = *(const bf16x8*)(bp + ks * 32);
;                 acc = __builtin_amdgcn_mfma_f32_16x16x32_bf16(av, bv, acc, 0, 0, 0);
;             }
;             const float bb = p.b_if[layer * 16 + r16];
; #pragma unroll
;             for (int r = 0; r < 4; ++r) pre[(wid * 16 + kq * 4 + r) * 17 + r16] = acc[r] + bb;
;         }
;         __syncthreads();
;         {
;             const int dir = wid >> 2, head = wid & 3;
;             const int p0 = dir ? 127 - 2 * lane : 2 * lane, p1 = dir ? 126 - 2 * lane : 2 * lane + 1;
;             const float i0 = pre[p0 * 17 + dir * 8 + head], f0 = pre[p0 * 17 + dir * 8 + 4 + head];
;             const float i1 = pre[p1 * 17 + dir * 8 + head], f1 = pre[p1 * 17 + dir * 8 + 4 + head];
;             const float l0 = fminf(f0, 0.f) - log1pf(__expf(-fabsf(f0))), l1 = fminf(f1, 0.f) - log1pf(__expf(-fabsf(f1)));
.LBB0_508:
	s_waitcnt vmcnt(0)
	v_lshl_add_u64 v[38:39], v[18:19], 0, s[0:1]
	v_lshl_add_u64 v[40:41], v[10:11], 0, s[0:1]
	global_load_dwordx4 v[30:33], v[38:39], off
	global_load_dwordx4 v[34:37], v[40:41], off offset:-256
	global_load_dwordx4 v[42:45], v[38:39], off offset:64
	global_load_dwordx4 v[46:49], v[40:41], off offset:-192
	global_load_dwordx4 v[50:53], v[38:39], off offset:128
	global_load_dwordx4 v[54:57], v[40:41], off offset:-128
	global_load_dwordx4 v[58:61], v[38:39], off offset:192
	global_load_dwordx4 v[62:65], v[40:41], off offset:-64
	global_load_dwordx4 v[66:69], v[38:39], off offset:256
	global_load_dwordx4 v[70:73], v[40:41], off
	global_load_dwordx4 v[74:77], v[38:39], off offset:320
	global_load_dwordx4 v[78:81], v[40:41], off offset:64
	global_load_dwordx4 v[82:85], v[38:39], off offset:384
	global_load_dwordx4 v[86:89], v[40:41], off offset:128
	global_load_dwordx4 v[90:93], v[38:39], off offset:448
	global_load_dwordx4 v[94:97], v[40:41], off offset:192
	s_add_u32 s0, s0, 0x200
	s_addc_u32 s1, s1, 0
	s_cmpk_eq_i32 s0, 0x800
	s_waitcnt vmcnt(14)
	v_mfma_f32_16x16x32_bf16 v[2:5], v[30:33], v[34:37], v[2:5]
	s_waitcnt vmcnt(12)
	v_mfma_f32_16x16x32_bf16 v[2:5], v[42:45], v[46:49], v[2:5]
	s_waitcnt vmcnt(10)
	v_mfma_f32_16x16x32_bf16 v[2:5], v[50:53], v[54:57], v[2:5]
	s_waitcnt vmcnt(8)
	v_mfma_f32_16x16x32_bf16 v[2:5], v[58:61], v[62:65], v[2:5]
	s_waitcnt vmcnt(6)
	v_mfma_f32_16x16x32_bf16 v[2:5], v[66:69], v[70:73], v[2:5]
	s_waitcnt vmcnt(4)
	v_mfma_f32_16x16x32_bf16 v[2:5], v[74:77], v[78:81], v[2:5]
	s_waitcnt vmcnt(2)
	v_mfma_f32_16x16x32_bf16 v[2:5], v[82:85], v[86:89], v[2:5]
	s_waitcnt vmcnt(0)
	v_mfma_f32_16x16x32_bf16 v[2:5], v[90:93], v[94:97], v[2:5]
	s_cbranch_scc0 .LBB0_508
	global_load_dword v15, v[8:9], off
	s_mov_b32 s0, 0xbfb8aa3b
	s_mov_b32 s1, 0x3f2aaaab
	s_mov_b32 s5, 0x3f317218
	s_mov_b32 s6, 0x7f800000
	s_mov_b32 s7, 0x33800000
	v_add_u32_e32 v14, s3, v14
	s_waitcnt vmcnt(0)
	v_add_f32_e32 v2, v2, v15
	v_add_f32_e32 v3, v3, v15
	ds_write2_b32 v28, v2, v3 offset1:17
	v_add_f32_e32 v2, v4, v15
	v_add_f32_e32 v3, v5, v15
	ds_write2_b32 v28, v2, v3 offset0:34 offset1:51
	s_waitcnt lgkmcnt(0)
	s_barrier
	ds_read2_b32 v[2:3], v20 offset1:4
	ds_read2_b32 v[4:5], v21 offset1:4
	s_waitcnt lgkmcnt(1)
	v_max_f32_e32 v15, v3, v3
	v_mul_f32_e64 v3, |v3|, s0
	v_exp_f32_e32 v3, v3
	v_min_f32_e32 v15, 0, v15
	v_add_f32_e32 v17, 1.0, v3
	v_add_f32_e32 v18, -1.0, v17
	v_sub_f32_e32 v19, v18, v17
	v_add_f32_e32 v19, 1.0, v19
	v_sub_f32_e32 v18, v3, v18
	v_add_f32_e32 v29, v18, v19
	v_frexp_mant_f32_e32 v18, v17
	v_cmp_gt_f32_e64 s[46:47], s1, v18
	v_cvt_f64_f32_e32 v[18:19], v17
	v_frexp_exp_i32_f64_e32 v18, v[18:19]
	v_subbrev_co_u32_e64 v18, s[46:47], 0, v18, s[46:47]
	v_sub_u32_e32 v19, 0, v18
	v_ldexp_f32 v17, v17, v19
	v_ldexp_f32 v19, v29, v19
	v_add_f32_e32 v29, -1.0, v17
	v_add_f32_e32 v30, 1.0, v29
	v_sub_f32_e32 v30, v17, v30
	v_add_f32_e32 v30, v19, v30
	v_add_f32_e32 v31, v29, v30
	v_sub_f32_e32 v29, v31, v29
	v_sub_f32_e32 v29, v30, v29
	v_add_f32_e32 v30, 1.0, v17
	v_add_f32_e32 v32, -1.0, v30
	v_sub_f32_e32 v17, v17, v32
	v_add_f32_e32 v17, v19, v17
	v_add_f32_e32 v19, v30, v17
	v_sub_f32_e32 v30, v19, v30
	v_sub_f32_e32 v17, v17, v30
	v_rcp_f32_e32 v30, v19
	v_cvt_f32_i32_e32 v18, v18
	v_cmp_neq_f32_e64 s[46:47], s6, v3
	v_mul_f32_e32 v32, v31, v30
	v_mul_f32_e32 v33, v19, v32
	v_fma_f32 v34, v32, v19, -v33
	v_fmac_f32_e32 v34, v32, v17
	v_add_f32_e32 v35, v33, v34
	v_sub_f32_e32 v36, v31, v35
	v_sub_f32_e32 v31, v31, v36
	v_sub_f32_e32 v33, v35, v33
	v_sub_f32_e32 v31, v31, v35
	v_add_f32_e32 v29, v29, v31
	v_sub_f32_e32 v31, v33, v34
	v_add_f32_e32 v29, v31, v29
	v_add_f32_e32 v31, v36, v29
	v_mul_f32_e32 v33, v30, v31
	v_mul_f32_e32 v34, v19, v33
	v_fma_f32 v19, v33, v19, -v34
	v_fmac_f32_e32 v19, v33, v17
	v_sub_f32_e32 v17, v36, v31
	v_add_f32_e32 v17, v29, v17
	v_add_f32_e32 v29, v34, v19
	v_sub_f32_e32 v35, v31, v29
	v_sub_f32_e32 v31, v31, v35
	v_sub_f32_e32 v34, v29, v34
	v_sub_f32_e32 v29, v31, v29
	v_add_f32_e32 v17, v17, v29
	v_sub_f32_e32 v19, v34, v19
	v_add_f32_e32 v17, v19, v17
	v_add_f32_e32 v19, v32, v33
	v_add_f32_e32 v17, v35, v17
	v_sub_f32_e32 v29, v19, v32
	v_mul_f32_e32 v17, v30, v17
	v_sub_f32_e32 v29, v33, v29
	v_add_f32_e32 v17, v29, v17
	v_mul_f32_e32 v32, 0x3f317218, v18
	v_add_f32_e32 v29, v19, v17
	v_fma_f32 v33, v18, s5, -v32
	v_mul_f32_e32 v30, v29, v29
	v_fmac_f32_e32 v33, 0xb102e308, v18
	v_sub_f32_e32 v18, v29, v19
	v_fmamk_f32 v31, v30, 0x3e9b6dac, v228
	v_sub_f32_e32 v17, v17, v18
	v_add_f32_e32 v18, v32, v33
	v_fmaak_f32 v31, v30, v31, 0x3f2aaada
	v_sub_f32_e32 v19, v18, v32
	v_ldexp_f32 v32, v29, 1
	v_mul_f32_e32 v29, v29, v30
	v_mul_f32_e32 v29, v29, v31
	v_add_f32_e32 v30, v32, v29
	v_sub_f32_e32 v31, v30, v32
	v_ldexp_f32 v17, v17, 1
	v_sub_f32_e32 v29, v29, v31
	v_add_f32_e32 v17, v17, v29
	v_add_f32_e32 v29, v30, v17
	v_sub_f32_e32 v30, v29, v30
	v_sub_f32_e32 v17, v17, v30
	v_add_f32_e32 v30, v18, v29
	v_sub_f32_e32 v31, v30, v18
	v_sub_f32_e32 v32, v30, v31
	v_sub_f32_e32 v19, v33, v19
	v_sub_f32_e32 v18, v18, v32
	v_sub_f32_e32 v29, v29, v31
	v_add_f32_e32 v18, v29, v18
	v_add_f32_e32 v29, v19, v17
	v_sub_f32_e32 v31, v29, v19
	v_sub_f32_e32 v32, v29, v31
	v_sub_f32_e32 v19, v19, v32
	v_sub_f32_e32 v17, v17, v31
	v_add_f32_e32 v18, v29, v18
	v_add_f32_e32 v17, v17, v19
	v_add_f32_e32 v19, v30, v18
	v_sub_f32_e32 v29, v19, v30
	v_sub_f32_e32 v18, v18, v29
	v_add_f32_e32 v17, v17, v18
	v_add_f32_e32 v17, v19, v17
	v_cndmask_b32_e64 v17, v230, v17, s[46:47]
	v_cmp_ngt_f32_e64 s[46:47], -1.0, v3
	s_nop 1
	v_cndmask_b32_e64 v17, v231, v17, s[46:47]
	v_cmp_neq_f32_e64 s[46:47], -1.0, v3
	s_nop 1
	v_cndmask_b32_e64 v17, v232, v17, s[46:47]
	v_cmp_lt_f32_e64 s[46:47], |v3|, s7
	s_nop 1
	v_cndmask_b32_e64 v3, v17, v3, s[46:47]
	v_sub_f32_e32 v3, v15, v3
	s_waitcnt lgkmcnt(0)
; DI void phase_gates2(const Params& p, unsigned char* smem, int layer, const bf16_t* xin, int nchunks, int tid) {
;     ...
;             const float l0 = fminf(f0, 0.f) - log1pf(__expf(-fabsf(f0))), l1 = fminf(f1, 0.f) - log1pf(__expf(-fabsf(f1)));
;             const float pair = l0 + l1;
;             float inc = pair;
; #pragma unroll
;             for (int d = 1; d < 64; d <<= 1) { const float t = __shfl_up(inc, d); if (lane >= d) inc += t; }
;             const float exc = inc - pair;
;             const float c0 = exc + l0, c1 = exc + pair;
;             const float b0 = i0 - c0, b1 = i1 - c1;
;             float mx = fmaxf(b0, b1);
; #pragma unroll
;             for (int d = 1; d < 64; d <<= 1) { const float t = __shfl_up(mx, d); if (lane >= d) mx = fmaxf(mx, t); }
;             float mexc = __shfl_up(mx, 1); if (lane == 0) mexc = -3.0e38f;
;             const float pm0 = fmaxf(mexc, b0), pm1 = fmaxf(pm0, b1);
;             float* gp = p.gates + ((size_t)(ch * 2 + dir) * 4 + head) * 384;
;             gp[p0] = b0; gp[128 + p0] = pm0; gp[256 + p0] = c0;
;             gp[p1] = b1; gp[128 + p1] = pm1; gp[256 + p1] = c1;
;         }
;         __syncthreads();
	v_max_f32_e32 v15, v5, v5
	v_mul_f32_e64 v5, |v5|, s0
	v_exp_f32_e32 v5, v5
	v_min_f32_e32 v15, 0, v15
	v_add_f32_e32 v29, 1.0, v5
	v_add_f32_e32 v17, -1.0, v29
	v_sub_f32_e32 v18, v17, v29
	v_add_f32_e32 v18, 1.0, v18
	v_sub_f32_e32 v17, v5, v17
	v_add_f32_e32 v30, v17, v18
	v_frexp_mant_f32_e32 v17, v29
	v_cvt_f64_f32_e32 v[18:19], v29
	v_cmp_gt_f32_e64 s[46:47], s1, v17
	v_frexp_exp_i32_f64_e32 v17, v[18:19]
	v_readlane_b32 s0, v253, 46
	v_subbrev_co_u32_e64 v17, s[46:47], 0, v17, s[46:47]
	v_sub_u32_e32 v18, 0, v17
	v_ldexp_f32 v19, v29, v18
	v_add_f32_e32 v29, -1.0, v19
	v_ldexp_f32 v18, v30, v18
	v_add_f32_e32 v30, 1.0, v29
	v_sub_f32_e32 v30, v19, v30
	v_add_f32_e32 v30, v18, v30
	v_add_f32_e32 v31, v29, v30
	v_sub_f32_e32 v29, v31, v29
	v_sub_f32_e32 v29, v30, v29
	v_add_f32_e32 v30, 1.0, v19
	v_add_f32_e32 v32, -1.0, v30
	v_sub_f32_e32 v19, v19, v32
	v_add_f32_e32 v18, v18, v19
	v_add_f32_e32 v19, v30, v18
	v_sub_f32_e32 v30, v19, v30
	v_sub_f32_e32 v18, v18, v30
	v_rcp_f32_e32 v30, v19
	v_cvt_f32_i32_e32 v17, v17
	v_cmp_neq_f32_e64 s[46:47], s6, v5
	v_readlane_b32 s1, v253, 47
	v_mul_f32_e32 v32, v31, v30
	v_mul_f32_e32 v33, v19, v32
	v_fma_f32 v34, v32, v19, -v33
	v_fmac_f32_e32 v34, v32, v18
	v_add_f32_e32 v35, v33, v34
	v_sub_f32_e32 v36, v31, v35
	v_sub_f32_e32 v31, v31, v36
	v_sub_f32_e32 v33, v35, v33
	v_sub_f32_e32 v31, v31, v35
	v_add_f32_e32 v29, v29, v31
	v_sub_f32_e32 v31, v33, v34
	v_add_f32_e32 v29, v31, v29
	v_add_f32_e32 v31, v36, v29
	v_mul_f32_e32 v33, v30, v31
	v_mul_f32_e32 v34, v19, v33
	v_fma_f32 v19, v33, v19, -v34
	v_fmac_f32_e32 v19, v33, v18
	v_sub_f32_e32 v18, v36, v31
	v_add_f32_e32 v18, v29, v18
	v_add_f32_e32 v29, v34, v19
	v_sub_f32_e32 v35, v31, v29
	v_sub_f32_e32 v31, v31, v35
	v_sub_f32_e32 v34, v29, v34
	v_sub_f32_e32 v29, v31, v29
	v_add_f32_e32 v18, v18, v29
	v_sub_f32_e32 v19, v34, v19
	v_add_f32_e32 v18, v19, v18
	v_add_f32_e32 v19, v32, v33
	v_add_f32_e32 v18, v35, v18
	v_sub_f32_e32 v29, v19, v32
	v_mul_f32_e32 v18, v30, v18
	v_sub_f32_e32 v29, v33, v29
	v_add_f32_e32 v18, v29, v18
	v_mul_f32_e32 v32, 0x3f317218, v17
	v_add_f32_e32 v29, v19, v18
	v_fma_f32 v33, v17, s5, -v32
	v_mul_f32_e32 v30, v29, v29
	v_fmac_f32_e32 v33, 0xb102e308, v17
	v_sub_f32_e32 v17, v29, v19
	v_fmamk_f32 v31, v30, 0x3e9b6dac, v228
	v_sub_f32_e32 v17, v18, v17
	v_add_f32_e32 v18, v32, v33
	v_fmaak_f32 v31, v30, v31, 0x3f2aaada
	v_sub_f32_e32 v19, v18, v32
	v_ldexp_f32 v32, v29, 1
	v_mul_f32_e32 v29, v29, v30
	v_mul_f32_e32 v29, v29, v31
	v_add_f32_e32 v30, v32, v29
	v_sub_f32_e32 v31, v30, v32
	v_ldexp_f32 v17, v17, 1
	v_sub_f32_e32 v29, v29, v31
	v_add_f32_e32 v17, v17, v29
	v_add_f32_e32 v29, v30, v17
	v_sub_f32_e32 v30, v29, v30
	v_sub_f32_e32 v17, v17, v30
	v_add_f32_e32 v30, v18, v29
	v_sub_f32_e32 v31, v30, v18
	v_sub_f32_e32 v32, v30, v31
	v_sub_f32_e32 v19, v33, v19
	v_sub_f32_e32 v18, v18, v32
	v_sub_f32_e32 v29, v29, v31
	v_add_f32_e32 v18, v29, v18
	v_add_f32_e32 v29, v19, v17
	v_sub_f32_e32 v31, v29, v19
	v_sub_f32_e32 v32, v29, v31
	v_sub_f32_e32 v19, v19, v32
	v_sub_f32_e32 v17, v17, v31
	v_add_f32_e32 v18, v29, v18
	v_add_f32_e32 v17, v17, v19
	v_add_f32_e32 v19, v30, v18
	v_sub_f32_e32 v29, v19, v30
	v_sub_f32_e32 v18, v18, v29
	v_add_f32_e32 v17, v17, v18
	v_add_f32_e32 v17, v19, v17
	v_cndmask_b32_e64 v17, v230, v17, s[46:47]
	v_cmp_ngt_f32_e64 s[46:47], -1.0, v5
	s_movk_i32 s5, 0x600
	s_nop 0
	v_cndmask_b32_e64 v17, v231, v17, s[46:47]
	v_cmp_neq_f32_e64 s[46:47], -1.0, v5
	s_nop 1
	v_cndmask_b32_e64 v17, v232, v17, s[46:47]
	v_cmp_lt_f32_e64 s[46:47], |v5|, s7
	s_nop 1
	v_cndmask_b32_e64 v5, v17, v5, s[46:47]
	v_sub_f32_e32 v5, v15, v5
	v_add_f32_e32 v5, v3, v5
	ds_bpermute_b32 v15, v22, v5
	s_waitcnt lgkmcnt(0)
	v_add_f32_e32 v15, v5, v15
	v_cndmask_b32_e32 v15, v15, v5, vcc
	ds_bpermute_b32 v17, v23, v15
	s_waitcnt lgkmcnt(0)
	v_add_f32_e32 v17, v15, v17
	v_cndmask_b32_e64 v15, v17, v15, s[36:37]
	ds_bpermute_b32 v17, v24, v15
	s_waitcnt lgkmcnt(0)
	v_add_f32_e32 v17, v15, v17
	v_cndmask_b32_e64 v15, v17, v15, s[38:39]
	ds_bpermute_b32 v17, v25, v15
	s_waitcnt lgkmcnt(0)
	v_add_f32_e32 v17, v15, v17
	v_cndmask_b32_e64 v15, v17, v15, s[40:41]
	ds_bpermute_b32 v17, v26, v15
	s_waitcnt lgkmcnt(0)
	v_add_f32_e32 v17, v15, v17
	v_cndmask_b32_e64 v15, v17, v15, s[42:43]
	ds_bpermute_b32 v17, v27, v15
	s_waitcnt lgkmcnt(0)
	v_add_f32_e32 v17, v15, v17
	v_cndmask_b32_e64 v15, v17, v15, s[44:45]
	v_sub_f32_e32 v15, v15, v5
	v_add_f32_e32 v17, v3, v15
	v_add_f32_e32 v15, v5, v15
	v_sub_f32_e32 v18, v2, v17
	v_sub_f32_e32 v19, v4, v15
	v_max_f32_e32 v2, v18, v19
	ds_bpermute_b32 v3, v22, v2
	s_waitcnt lgkmcnt(0)
	v_max_f32_e32 v3, v3, v3
	v_max_f32_e32 v3, v2, v3
	v_cndmask_b32_e32 v2, v3, v2, vcc
	ds_bpermute_b32 v3, v23, v2
	s_waitcnt lgkmcnt(0)
	v_max_f32_e32 v3, v3, v3
	v_max_f32_e32 v3, v2, v3
	v_cndmask_b32_e64 v2, v3, v2, s[36:37]
	ds_bpermute_b32 v3, v24, v2
	s_waitcnt lgkmcnt(0)
	v_max_f32_e32 v3, v3, v3
	v_max_f32_e32 v3, v2, v3
	v_cndmask_b32_e64 v2, v3, v2, s[38:39]
	ds_bpermute_b32 v3, v25, v2
	s_waitcnt lgkmcnt(0)
	v_max_f32_e32 v3, v3, v3
	v_max_f32_e32 v3, v2, v3
	v_cndmask_b32_e64 v2, v3, v2, s[40:41]
	ds_bpermute_b32 v3, v26, v2
	s_waitcnt lgkmcnt(0)
	v_max_f32_e32 v3, v3, v3
	v_max_f32_e32 v3, v2, v3
	v_cndmask_b32_e64 v2, v3, v2, s[42:43]
	ds_bpermute_b32 v3, v27, v2
	v_max_f32_e32 v4, v2, v2
	s_waitcnt lgkmcnt(0)
	v_max_f32_e32 v3, v3, v3
	v_max_f32_e32 v3, v4, v3
	v_cndmask_b32_e64 v2, v3, v2, s[44:45]
	ds_bpermute_b32 v2, v22, v2
	v_mov_b64_e32 v[4:5], s[0:1]
	s_waitcnt lgkmcnt(0)
	v_cndmask_b32_e32 v2, v2, v233, vcc
	v_max_f32_e32 v2, v2, v2
	v_max_f32_e32 v29, v2, v18
	v_lshl_add_u32 v2, s4, 1, v7
	v_ashrrev_i32_e32 v3, 31, v2
	v_lshlrev_b64 v[2:3], 2, v[2:3]
	v_or_b32_e32 v2, v2, v6
	v_mad_u64_u32 v[4:5], s[0:1], v2, s5, v[4:5]
	v_mad_i32_i24 v5, v3, s5, v5
	v_lshl_add_u64 v[2:3], v[4:5], 0, v[0:1]
	global_store_dword v[2:3], v18, off
	global_store_dword v[2:3], v29, off offset:512
	global_store_dword v[2:3], v17, off offset:1024
	v_mov_b32_e32 v17, v1
	s_add_i32 s4, s4, s48
	v_lshl_add_u64 v[2:3], v[4:5], 0, v[16:17]
	s_cmp_ge_i32 s4, s2
	v_max_f32_e32 v30, v29, v19
	global_store_dword v[2:3], v19, off
	global_store_dword v[2:3], v30, off offset:512
	global_store_dword v[2:3], v15, off offset:1024
	s_barrier
	s_cbranch_scc0 .LBB0_507
	s_mov_b32 s67, s9
